# bh1 + grid barrier early acquire: L1 invalidate issued at arrival (overlaps the wait), dead per-XCD release bump dropped
# speedup vs baseline: 1.0070x; 1.0070x over previous
; __device__ __forceinline__ unsigned xb_ld(unsigned* p)              { return __hip_atomic_load(p, __ATOMIC_RELAXED, __HIP_MEMORY_SCOPE_AGENT); }
; __device__ __forceinline__ unsigned xb_add(unsigned* p, unsigned v) { return __hip_atomic_fetch_add(p, v, __ATOMIC_RELAXED, __HIP_MEMORY_SCOPE_AGENT); }
; #define XB_SPIN(cond, bar) do { unsigned _sp = 0; while (cond) { __builtin_amdgcn_s_sleep(1); \
;     if ((++_sp & 255u) == 0u) { if (xb_ld(&(bar)[XB_TMO])) break; if (_sp > XB_SPIN_CAP) { atomicAdd(&(bar)[XB_TMO], 1u); break; } } } } while (0)
; __device__ __forceinline__ void xcd_barrier(const XcdBarrier& b, int tid) {
;     ...
;         const unsigned old = xb_add(&bar[XB_XSUB(b.x)], 1u);
;         const unsigned gen = old / nloc;
;         if (old + 1u == (gen + 1u) * nloc) {
;             __builtin_amdgcn_fence(__ATOMIC_RELEASE, "agent");
;             asm volatile("s_waitcnt vmcnt(0)" ::: "memory");
;             const unsigned og = xb_add(&bar[XB_TOP], 1u);
;             const unsigned tg = og / nx;
;             if (og + 1u == (tg + 1u) * nx) xb_add(&bar[XB_TOPGEN], 1u);
;             else XB_SPIN(xb_ld(&bar[XB_TOPGEN]) == tg, bar);
;             __builtin_amdgcn_fence(__ATOMIC_ACQUIRE, "agent");
;             xb_add(&bar[XB_XGEN(b.x)], 1u);
;             asm volatile("s_waitcnt vmcnt(0)" ::: "memory");
;         } else {
;             XB_SPIN(xb_ld(&bar[XB_XGEN(b.x)]) == gen, bar);
;             __builtin_amdgcn_fence(__ATOMIC_ACQUIRE, "agent");
.LBB0_105:
	s_or_b64 exec, exec, s[12:13]
	v_cvt_f32_u32_e32 v5, v3
	s_waitcnt vmcnt(0)
	buffer_inv sc1
	v_readfirstlane_b32 s3, v4
	v_sub_u32_e32 v4, 0, v3
	v_rcp_iflag_f32_e32 v5, v5
	v_add_u32_e32 v6, s3, v2
	v_mul_f32_e32 v5, 0x4f7ffffe, v5
	v_cvt_u32_f32_e32 v5, v5
	v_mul_lo_u32 v2, v4, v5
	v_mul_hi_u32 v2, v5, v2
	v_add_u32_e32 v2, v5, v2
	v_mul_hi_u32 v2, v6, v2
	v_mul_lo_u32 v4, v2, v3
	v_sub_u32_e32 v4, v6, v4
	v_add_u32_e32 v5, 1, v2
	v_cmp_ge_u32_e32 vcc, v4, v3
	s_nop 1
	v_cndmask_b32_e32 v2, v2, v5, vcc
	v_sub_u32_e32 v5, v4, v3
	v_cndmask_b32_e32 v4, v4, v5, vcc
	v_add_u32_e32 v5, 1, v2
	v_cmp_ge_u32_e32 vcc, v4, v3
	v_add_u32_e32 v4, 1, v6
	s_nop 0
	v_cndmask_b32_e32 v2, v2, v5, vcc
	v_mul_lo_u32 v5, v3, v2
	v_add_u32_e32 v3, v5, v3
	v_cmp_ne_u32_e32 vcc, v4, v3
	s_and_saveexec_b64 s[10:11], vcc
	s_xor_b64 s[10:11], exec, s[10:11]
	s_cbranch_execz .LBB0_119
	s_waitcnt lgkmcnt(0)
	v_mov_b32_e32 v1, 0x3100
	global_load_dword v1, v1, s[6:7] offset:1024 sc1
	s_add_u32 s14, s6, 0x3500
	s_addc_u32 s15, s7, 0
	s_waitcnt vmcnt(0)
	v_cmp_eq_u32_e32 vcc, v1, v2
	s_and_saveexec_b64 s[12:13], vcc
	s_cbranch_execz .LBB0_118
	s_mov_b32 s3, 1
	s_mov_b64 s[16:17], 0
	v_mov_b32_e32 v1, 0
	s_branch .LBB0_109

; __device__ __forceinline__ unsigned xb_ld(unsigned* p)              { return __hip_atomic_load(p, __ATOMIC_RELAXED, __HIP_MEMORY_SCOPE_AGENT); }
; #define XB_SPIN(cond, bar) do { unsigned _sp = 0; while (cond) { __builtin_amdgcn_s_sleep(1); \
;     if ((++_sp & 255u) == 0u) { if (xb_ld(&(bar)[XB_TMO])) break; if (_sp > XB_SPIN_CAP) { atomicAdd(&(bar)[XB_TMO], 1u); break; } } } } while (0)
; __device__ __forceinline__ void xcd_barrier(const XcdBarrier& b, int tid) {
;     ...
;             XB_SPIN(xb_ld(&bar[XB_XGEN(b.x)]) == gen, bar);
;             __builtin_amdgcn_fence(__ATOMIC_ACQUIRE, "agent");
;             asm volatile("s_waitcnt vmcnt(0)" ::: "memory");
.LBB0_118:
	s_or_b64 exec, exec, s[12:13]
	s_waitcnt vmcnt(0)
	s_waitcnt vmcnt(0)

; __device__ __forceinline__ unsigned xb_ld(unsigned* p)              { return __hip_atomic_load(p, __ATOMIC_RELAXED, __HIP_MEMORY_SCOPE_AGENT); }
; __device__ __forceinline__ unsigned xb_add(unsigned* p, unsigned v) { return __hip_atomic_fetch_add(p, v, __ATOMIC_RELAXED, __HIP_MEMORY_SCOPE_AGENT); }
; #define XB_SPIN(cond, bar) do { unsigned _sp = 0; while (cond) { __builtin_amdgcn_s_sleep(1); \
;     if ((++_sp & 255u) == 0u) { if (xb_ld(&(bar)[XB_TMO])) break; if (_sp > XB_SPIN_CAP) { atomicAdd(&(bar)[XB_TMO], 1u); break; } } } } while (0)
; __device__ __forceinline__ void xcd_barrier(const XcdBarrier& b, int tid) {
;     ...
;             if (og + 1u == (tg + 1u) * nx) xb_add(&bar[XB_TOPGEN], 1u);
;             else XB_SPIN(xb_ld(&bar[XB_TOPGEN]) == tg, bar);
;             __builtin_amdgcn_fence(__ATOMIC_ACQUIRE, "agent");
;             xb_add(&bar[XB_XGEN(b.x)], 1u);
;             asm volatile("s_waitcnt vmcnt(0)" ::: "memory");
.LBB0_136:
	s_or_b64 exec, exec, s[6:7]
	s_mov_b64 s[6:7], exec
	v_mbcnt_lo_u32_b32 v1, s6, 0
	v_mbcnt_hi_u32_b32 v1, s7, v1
	v_cmp_eq_u32_e32 vcc, 0, v1
	s_waitcnt vmcnt(0)
	s_and_saveexec_b64 s[10:11], vcc
	s_cbranch_execz .LBB0_138
	s_bcnt1_i32_b64 s3, s[6:7]
	v_mov_b32_e32 v1, 0x2000
	v_mov_b32_e32 v2, s3

; __device__ __forceinline__ unsigned xb_ld(unsigned* p)              { return __hip_atomic_load(p, __ATOMIC_RELAXED, __HIP_MEMORY_SCOPE_AGENT); }
; __device__ __forceinline__ unsigned xb_add(unsigned* p, unsigned v) { return __hip_atomic_fetch_add(p, v, __ATOMIC_RELAXED, __HIP_MEMORY_SCOPE_AGENT); }
; #define XB_SPIN(cond, bar) do { unsigned _sp = 0; while (cond) { __builtin_amdgcn_s_sleep(1); \
;     if ((++_sp & 255u) == 0u) { if (xb_ld(&(bar)[XB_TMO])) break; if (_sp > XB_SPIN_CAP) { atomicAdd(&(bar)[XB_TMO], 1u); break; } } } } while (0)
; __device__ __forceinline__ void xcd_barrier(const XcdBarrier& b, int tid) {
;     ...
;         const unsigned old = xb_add(&bar[XB_XSUB(b.x)], 1u);
;         const unsigned gen = old / nloc;
;         if (old + 1u == (gen + 1u) * nloc) {
;             __builtin_amdgcn_fence(__ATOMIC_RELEASE, "agent");
;             asm volatile("s_waitcnt vmcnt(0)" ::: "memory");
;             const unsigned og = xb_add(&bar[XB_TOP], 1u);
;             const unsigned tg = og / nx;
;             if (og + 1u == (tg + 1u) * nx) xb_add(&bar[XB_TOPGEN], 1u);
;             else XB_SPIN(xb_ld(&bar[XB_TOPGEN]) == tg, bar);
;             __builtin_amdgcn_fence(__ATOMIC_ACQUIRE, "agent");
;             xb_add(&bar[XB_XGEN(b.x)], 1u);
;             asm volatile("s_waitcnt vmcnt(0)" ::: "memory");
;         } else {
;             XB_SPIN(xb_ld(&bar[XB_XGEN(b.x)]) == gen, bar);
;             __builtin_amdgcn_fence(__ATOMIC_ACQUIRE, "agent");
.LBB0_378:
	s_or_b64 exec, exec, s[10:11]
	v_cvt_f32_u32_e32 v5, v3
	s_waitcnt vmcnt(0)
	buffer_inv sc1
	v_readfirstlane_b32 s3, v4
	v_sub_u32_e32 v4, 0, v3
	v_rcp_iflag_f32_e32 v5, v5
	v_add_u32_e32 v6, s3, v2
	v_mul_f32_e32 v5, 0x4f7ffffe, v5
	v_cvt_u32_f32_e32 v5, v5
	v_mul_lo_u32 v2, v4, v5
	v_mul_hi_u32 v2, v5, v2
	v_add_u32_e32 v2, v5, v2
	v_mul_hi_u32 v2, v6, v2
	v_mul_lo_u32 v4, v2, v3
	v_sub_u32_e32 v4, v6, v4
	v_add_u32_e32 v5, 1, v2
	v_cmp_ge_u32_e32 vcc, v4, v3
	s_nop 1
	v_cndmask_b32_e32 v2, v2, v5, vcc
	v_sub_u32_e32 v5, v4, v3
	v_cndmask_b32_e32 v4, v4, v5, vcc
	v_add_u32_e32 v5, 1, v2
	v_cmp_ge_u32_e32 vcc, v4, v3
	v_add_u32_e32 v4, 1, v6
	s_nop 0
	v_cndmask_b32_e32 v2, v2, v5, vcc
	v_mul_lo_u32 v5, v3, v2
	v_add_u32_e32 v3, v5, v3
	v_cmp_ne_u32_e32 vcc, v4, v3
	s_and_saveexec_b64 s[8:9], vcc
	s_xor_b64 s[8:9], exec, s[8:9]
	s_cbranch_execz .LBB0_392
	s_waitcnt lgkmcnt(0)
	v_mov_b32_e32 v1, 0x3100
	global_load_dword v1, v1, s[4:5] offset:1024 sc1
	s_add_u32 s12, s4, 0x3500
	s_addc_u32 s13, s5, 0
	s_waitcnt vmcnt(0)
	v_cmp_eq_u32_e32 vcc, v1, v2
	s_and_saveexec_b64 s[10:11], vcc
	s_cbranch_execz .LBB0_391
	s_mov_b32 s3, 1
	s_mov_b64 s[14:15], 0
	v_mov_b32_e32 v1, 0
	s_branch .LBB0_382

; __device__ __forceinline__ unsigned xb_ld(unsigned* p)              { return __hip_atomic_load(p, __ATOMIC_RELAXED, __HIP_MEMORY_SCOPE_AGENT); }
; #define XB_SPIN(cond, bar) do { unsigned _sp = 0; while (cond) { __builtin_amdgcn_s_sleep(1); \
;     if ((++_sp & 255u) == 0u) { if (xb_ld(&(bar)[XB_TMO])) break; if (_sp > XB_SPIN_CAP) { atomicAdd(&(bar)[XB_TMO], 1u); break; } } } } while (0)
; __device__ __forceinline__ void xcd_barrier(const XcdBarrier& b, int tid) {
;     ...
;             XB_SPIN(xb_ld(&bar[XB_XGEN(b.x)]) == gen, bar);
;             __builtin_amdgcn_fence(__ATOMIC_ACQUIRE, "agent");
;             asm volatile("s_waitcnt vmcnt(0)" ::: "memory");
.LBB0_391:
	s_or_b64 exec, exec, s[10:11]
	s_waitcnt vmcnt(0)
	s_waitcnt vmcnt(0)

; __device__ __forceinline__ unsigned xb_ld(unsigned* p)              { return __hip_atomic_load(p, __ATOMIC_RELAXED, __HIP_MEMORY_SCOPE_AGENT); }
; __device__ __forceinline__ unsigned xb_add(unsigned* p, unsigned v) { return __hip_atomic_fetch_add(p, v, __ATOMIC_RELAXED, __HIP_MEMORY_SCOPE_AGENT); }
; #define XB_SPIN(cond, bar) do { unsigned _sp = 0; while (cond) { __builtin_amdgcn_s_sleep(1); \
;     if ((++_sp & 255u) == 0u) { if (xb_ld(&(bar)[XB_TMO])) break; if (_sp > XB_SPIN_CAP) { atomicAdd(&(bar)[XB_TMO], 1u); break; } } } } while (0)
; __device__ __forceinline__ void xcd_barrier(const XcdBarrier& b, int tid) {
;     ...
;             if (og + 1u == (tg + 1u) * nx) xb_add(&bar[XB_TOPGEN], 1u);
;             else XB_SPIN(xb_ld(&bar[XB_TOPGEN]) == tg, bar);
;             __builtin_amdgcn_fence(__ATOMIC_ACQUIRE, "agent");
;             xb_add(&bar[XB_XGEN(b.x)], 1u);
;             asm volatile("s_waitcnt vmcnt(0)" ::: "memory");
.LBB0_409:
	s_or_b64 exec, exec, s[4:5]
	s_mov_b64 s[4:5], exec
	v_mbcnt_lo_u32_b32 v1, s4, 0
	v_mbcnt_hi_u32_b32 v1, s5, v1
	v_cmp_eq_u32_e32 vcc, 0, v1
	s_waitcnt vmcnt(0)
	s_and_saveexec_b64 s[8:9], vcc
	s_cbranch_execz .LBB0_411
	s_bcnt1_i32_b64 s3, s[4:5]
	v_mov_b32_e32 v1, 0x2000
	v_mov_b32_e32 v2, s3
